# compressed branch as a loop over resident tiles (all tiles loaded in one round, both query sub-tiles per trip, rotating importance accumulators) to cut instruction footprint
# baseline (speedup 1.0000x reference)
; __device__ __forceinline__ float bf2f(bf16_t v) { return __uint_as_float(((unsigned)v) << 16); }
; __device__ __forceinline__ float sigmoidf_(float x) { return __builtin_amdgcn_rcpf(1.0f + __expf(-x)); }
; __device__ __forceinline__ void nsa_unit(LAS unsigned char* lds, const Ctx& P, int l, int b, int hkv, int tb) {
;     ...
;     auto load2 = [&](const bf16_t* ksrc, const bf16_t* vsrc, size_t ld, int p0a, int p0b, bool hasb, int pmax) {
;         TileRegs ra, rb; tile_issue(ra, tid, ksrc, vsrc, ld, p0a, pmax); if (hasb) tile_issue(rb, tid, ksrc, vsrc, ld, p0b, pmax);
;         tile_commit(ra, tid, KV, KV + 4608); if (hasb) tile_commit(rb, tid, KV + 9216, KV + 9216 + 4608); };
; #pragma unroll 1
;     for (int sb = 0; sb < 2; ++sb) {
;         f32x4 o[4], oi[4]; float m = NEGBIG, lsum = 0.f;
; #pragma unroll
;         for (int dt = 0; dt < 4; ++dt) { o[dt] = (f32x4){0.f, 0.f, 0.f, 0.f}; oi[dt] = (f32x4){0.f, 0.f, 0.f, 0.f}; }
;         bf16x8 ovA[2], ovB[2];
; #pragma unroll
;         for (int st = 0; st < 2; ++st)
; #pragma unroll
;             for (int j = 0; j < 8; ++j) { const int nl = 32 * st + (j < 4 ? 4 * i + j : 16 + 4 * i + (j - 4));
;                 float a = 0.f; if ((nl >> 2) == c) a = ((nl & 3) == 3) ? 0.5f : 1.0f; else if ((nl >> 2) == c - 1 && (nl & 3) == 3) a = 0.5f;
;                 const float bb = (c == 0 && nl == 63) ? 0.5f : 0.f;
;                 ovA[st][j] = (short)(__float_as_uint(a) >> 16); ovB[st][j] = (short)(__float_as_uint(bb) >> 16); }
;         const int ntile = ((t0 >> 4) + 2) / 64 + 1;
;         const int tqs = t0 + 32 * th + 16 * sb + c;
;         bf16x8 qs[2];
; #pragma unroll
;         for (int ks = 0; ks < 2; ++ks) qs[ks] = load_q_scaled(H + ((size_t)b * SEQ + tqs) * LDH + C_Q + hq * 64 + ks * 32 + 8 * i, 0.125f);
; #pragma unroll
;         for (int pr = 0; pr < 2; ++pr) if (2 * pr < ntile) {
;             const bool hasb = 2 * pr + 1 < ntile;
;             __syncthreads();
;             load2(KC, VC, 64, 128 * pr, 128 * pr + 64, hasb, 255);
;     ...
;         const float g0 = sigmoidf_(bf2f(H[((size_t)b * SEQ + tqs) * LDH + C_GL + hq]) + P.in[21][l * 48 + hq]) * inv;
.LBB0_203:
	v_mov_b32_e32 v65, s74
	ds_read_b64 v[66:67], v65
	v_lshlrev_b32_e32 v86, 1, v96
	v_add_u32_e32 v86, 0x5400, v86
	v_add_co_u32_e32 v62, vcc, v86, v128
	s_nop 1
	v_addc_co_u32_e32 v63, vcc, 0, v129, vcc
	global_load_ushort v108, v[62:63], off
	v_lshlrev_b32_e32 v86, 1, v96
	v_add_u32_e32 v86, 0x5400, v86
	v_add_co_u32_e32 v62, vcc, v86, v122
	s_nop 1
	v_addc_co_u32_e32 v63, vcc, 0, v123, vcc
	global_load_ushort v109, v[62:63], off
	s_lshr_b32 s26, s55, 4
	s_add_u32 s26, s26, 2
	s_lshr_b32 s26, s26, 6
	s_add_u32 s26, s26, 1
	s_lshl_b32 s44, s61, 2
	s_or_b32 s44, s44, s60
	s_lshl_b32 s44, s44, 15
	s_add_u32 s44, s44, 0x33203000
	s_add_u32 s20, s68, s44
	s_addc_u32 s21, s69, 0
	v_lshlrev_b32_e32 v139, 4, v234
	v_mov_b32_e32 v86, v139
	v_add_u32_e32 v87, 0x80000, v86
	global_load_dwordx4 v[198:201], v86, s[20:21]
	global_load_dwordx4 v[202:205], v87, s[20:21]
	s_cmp_lt_u32 s26, 2
	s_cbranch_scc1 .Lcm_ld_1
	v_add_u32_e32 v86, 0x2000, v139
	v_add_u32_e32 v87, 0x80000, v86
	global_load_dwordx4 v[206:209], v86, s[20:21]
	global_load_dwordx4 v[210:213], v87, s[20:21]
	s_cmp_lt_u32 s26, 3
	s_cbranch_scc1 .Lcm_ld_1
	v_add_u32_e32 v86, 0x4000, v139
	v_add_u32_e32 v87, 0x80000, v86
	global_load_dwordx4 v[214:217], v86, s[20:21]
	global_load_dwordx4 v[218:221], v87, s[20:21]
	s_cmp_lt_u32 s26, 4
	s_cbranch_scc1 .Lcm_ld_1
	v_add_u32_e32 v86, 0x6000, v139
	v_add_u32_e32 v87, 0x80000, v86
	global_load_dwordx4 v[222:225], v86, s[20:21]
	global_load_dwordx4 v[226:229], v87, s[20:21]
.Lcm_ld_1:
	v_add_u32_e32 v190, v150, v148
	v_lshrrev_b32_e32 v86, 2, v97
	v_lshl_add_u32 v86, v103, 2, v86
	v_mul_u32_u24_e32 v86, 0x90, v86
	v_and_b32_e32 v87, 3, v97
	v_lshl_add_u32 v191, v87, 3, v86
	v_mov_b32_e32 v192, v190
	v_mov_b32_e32 v193, v191
	v_add_u32_e32 v194, 0xc000, v146
	v_add_u32_e32 v86, 0, v103
	v_cmp_eq_u32_e32 vcc, v86, v97
	v_mov_b32_e32 v87, 0x3f803f80
	v_add_u32_e32 v89, 1, v86
	s_nop 1
	v_cndmask_b32_e32 v160, 0, v87, vcc
	v_mov_b32_e32 v87, 0x3f80
	v_cndmask_b32_e32 v88, 0, v87, vcc
	v_cmp_eq_u32_e64 s[0:1], v89, v97
	v_mov_b32_e32 v87, 0x3f000000
	s_or_b64 vcc, vcc, s[0:1]
	s_nop 3
	v_cndmask_b32_e32 v87, 0, v87, vcc
	v_or_b32_e32 v161, v87, v88
	v_add_u32_e32 v86, 4, v103
	v_cmp_eq_u32_e32 vcc, v86, v97
	v_mov_b32_e32 v87, 0x3f803f80
	v_add_u32_e32 v89, 1, v86
	s_nop 1
	v_cndmask_b32_e32 v162, 0, v87, vcc
	v_mov_b32_e32 v87, 0x3f80
	v_cndmask_b32_e32 v88, 0, v87, vcc
	v_cmp_eq_u32_e64 s[0:1], v89, v97
	v_mov_b32_e32 v87, 0x3f000000
	s_or_b64 vcc, vcc, s[0:1]
	s_nop 3
	v_cndmask_b32_e32 v87, 0, v87, vcc
	v_or_b32_e32 v163, v87, v88
	v_add_u32_e32 v86, 8, v103
	v_cmp_eq_u32_e32 vcc, v86, v97
	v_mov_b32_e32 v87, 0x3f803f80
	v_add_u32_e32 v89, 1, v86
	s_nop 1
	v_cndmask_b32_e32 v170, 0, v87, vcc
	v_mov_b32_e32 v87, 0x3f80
	v_cndmask_b32_e32 v88, 0, v87, vcc
	v_cmp_eq_u32_e64 s[0:1], v89, v97
	v_mov_b32_e32 v87, 0x3f000000
	s_or_b64 vcc, vcc, s[0:1]
	s_nop 3
	v_cndmask_b32_e32 v87, 0, v87, vcc
	v_or_b32_e32 v171, v87, v88
	v_add_u32_e32 v86, 12, v103
	v_cmp_eq_u32_e32 vcc, v86, v97
	v_mov_b32_e32 v87, 0x3f803f80
	v_add_u32_e32 v89, 1, v86
	s_nop 1
	v_cndmask_b32_e32 v172, 0, v87, vcc
	v_mov_b32_e32 v87, 0x3f80
	v_cndmask_b32_e32 v88, 0, v87, vcc
	v_cmp_eq_u32_e64 s[0:1], v89, v97
	v_mov_b32_e32 v87, 0x3f000000
	s_or_b64 vcc, vcc, s[0:1]
	s_nop 3
	v_cndmask_b32_e32 v87, 0, v87, vcc
	v_or_b32_e32 v173, v87, v88
	v_mov_b32_e32 v230, 0
	v_mov_b32_e32 v231, 0
	v_mov_b32_e32 v232, 0
	v_cmp_eq_u32_e32 vcc, 0, v97
	v_cmp_eq_u32_e64 s[0:1], 3, v103
	v_mov_b32_e32 v87, 0x3f000000
	s_and_b64 vcc, vcc, s[0:1]
	s_nop 3
	v_cndmask_b32_e32 v233, 0, v87, vcc
	v_mov_b32_e32 v30, 0
	v_mov_b32_e32 v46, 0
	v_mov_b32_e32 v31, 0
	v_mov_b32_e32 v47, 0
	v_mov_b32_e32 v32, 0
	v_mov_b32_e32 v48, 0
	v_mov_b32_e32 v33, 0
	v_mov_b32_e32 v49, 0
	v_mov_b32_e32 v34, 0
	v_mov_b32_e32 v50, 0
	v_mov_b32_e32 v35, 0
	v_mov_b32_e32 v51, 0
	v_mov_b32_e32 v36, 0
	v_mov_b32_e32 v52, 0
	v_mov_b32_e32 v37, 0
	v_mov_b32_e32 v53, 0
	v_mov_b32_e32 v38, 0
	v_mov_b32_e32 v54, 0
	v_mov_b32_e32 v39, 0
	v_mov_b32_e32 v55, 0
	v_mov_b32_e32 v40, 0
	v_mov_b32_e32 v56, 0
	v_mov_b32_e32 v41, 0
	v_mov_b32_e32 v57, 0
	v_mov_b32_e32 v42, 0
	v_mov_b32_e32 v58, 0
	v_mov_b32_e32 v43, 0
	v_mov_b32_e32 v59, 0
	v_mov_b32_e32 v44, 0
	v_mov_b32_e32 v60, 0
	v_mov_b32_e32 v45, 0
	v_mov_b32_e32 v61, 0
	v_mov_b32_e32 v137, 0xf149f2ca
	v_mov_b32_e32 v138, 0
	v_mov_b32_e32 v174, 0
	v_mov_b32_e32 v18, 0
	v_mov_b32_e32 v175, 0
	v_mov_b32_e32 v19, 0
	v_mov_b32_e32 v176, 0
	v_mov_b32_e32 v20, 0
	v_mov_b32_e32 v177, 0
	v_mov_b32_e32 v21, 0
	v_mov_b32_e32 v178, 0
	v_mov_b32_e32 v22, 0
	v_mov_b32_e32 v179, 0
	v_mov_b32_e32 v23, 0
	v_mov_b32_e32 v180, 0
	v_mov_b32_e32 v24, 0
	v_mov_b32_e32 v181, 0
	v_mov_b32_e32 v25, 0
	v_mov_b32_e32 v182, 0
	v_mov_b32_e32 v26, 0
	v_mov_b32_e32 v183, 0
	v_mov_b32_e32 v27, 0
	v_mov_b32_e32 v184, 0
	v_mov_b32_e32 v28, 0
	v_mov_b32_e32 v185, 0
	v_mov_b32_e32 v29, 0
	v_mov_b32_e32 v186, 0
	v_mov_b32_e32 v104, 0
	v_mov_b32_e32 v187, 0
	v_mov_b32_e32 v105, 0
	v_mov_b32_e32 v188, 0
	v_mov_b32_e32 v106, 0
	v_mov_b32_e32 v189, 0
	v_mov_b32_e32 v107, 0
	v_mov_b32_e32 v195, 0xf149f2ca
	v_mov_b32_e32 v196, 0
	s_waitcnt lgkmcnt(0)
	v_readfirstlane_b32 s0, v66
	v_readfirstlane_b32 s1, v67
	s_nop 4
	s_nop 0
	global_load_dword v110, v158, s[0:1]
	s_barrier
	s_waitcnt vmcnt(0)
	ds_write_b128 v146, v[198:201] offset:16384
	ds_write_b128 v146, v[202:205] offset:25600
	s_cmp_lt_u32 s26, 2
	s_cbranch_scc1 .Lcm_wd_2
	ds_write_b128 v146, v[206:209] offset:34816
	ds_write_b128 v146, v[210:213] offset:44032
	s_cmp_lt_u32 s26, 3
	s_cbranch_scc1 .Lcm_wd_2
	ds_write_b128 v194, v[214:217] offset:4096
	ds_write_b128 v194, v[218:221] offset:13312
	s_cmp_lt_u32 s26, 4
	s_cbranch_scc1 .Lcm_wd_2
	ds_write_b128 v194, v[222:225] offset:22528
	ds_write_b128 v194, v[226:229] offset:31744
; #define LAS __attribute__((address_space(3)))
; __device__ __forceinline__ f32x4 mfma16(bf16x8 a, bf16x8 b, f32x4 c) { return __builtin_amdgcn_mfma_f32_16x16x32_bf16(a, b, c, 0, 0, 0); }
; template <int D, class SF>
; __device__ __forceinline__ void attn_step(const bf16x8 (&qf)[D / 32], const LAS bf16_t* Ks, const LAS bf16_t* Vt, f32x4 (&o)[D / 16], float& m, float& lsum, float& alpha_out, bf16x8& pf0_out, bf16x8& pf1_out, const int lane, SF sf) {
;     ...
;     for (int ks = 0; ks < D / 32; ++ks) {
; #pragma unroll
;         for (int t = 0; t < 4; ++t) { const bf16x8 kf = *(const LAS bf16x8*)(Ks + (16 * t + c) * KSTR + ks * 32 + 8 * i); s[t] = mfma16(kf, qf[ks], s[t]); }
;     }
;     float v[16];
; #pragma unroll
;     for (int t = 0; t < 4; ++t)
; #pragma unroll
;         for (int r = 0; r < 4; ++r) v[4 * t + r] = sf(16 * t + 4 * i + r, s[t][r]);
; __device__ __forceinline__ void nsa_unit(LAS unsigned char* lds, const Ctx& P, int l, int b, int hkv, int tb) {
;     ...
;             for (int sl = 0; sl < 2; ++sl) if (sl == 0 || hasb) {
;                 const int kt = 2 * pr + sl; const LAS bf16_t* Ks = KV + sl * 9216; const LAS bf16_t* Vt = Ks + 4608; const int nb = kt * 64;
;                 attn_step<64>(qs, Ks, Vt, o, m, lsum, alpha, pf, pf1, lane,
;                     [&](int kk, float s) { const int dist = tqs - (16 * (nb + kk) + 31); return dist >= 0 ? s * LOG2E + lut[min((unsigned)dist, 1023u)] : NEGBIG; });
.Lcm_wd_2:
	s_mov_b32 s4, 0
	s_mov_b32 s5, 31
	s_waitcnt lgkmcnt(0)
	s_barrier
.Lcm_top_3:
	v_lshlrev_b32_e32 v86, 6, v103
	v_sub_u32_e32 v86, v130, v86
	v_subrev_u32_e32 v86, s5, v86
	v_subrev_u32_e32 v78, 0, v86
	v_min_u32_e32 v78, 0x3ff, v78
	v_lshl_add_u32 v78, v78, 2, v131
	ds_read_b32 v78, v78
	v_subrev_u32_e32 v79, 16, v86
	v_min_u32_e32 v79, 0x3ff, v79
	v_lshl_add_u32 v79, v79, 2, v131
	ds_read_b32 v79, v79
	v_subrev_u32_e32 v80, 32, v86
	v_min_u32_e32 v80, 0x3ff, v80
	v_lshl_add_u32 v80, v80, 2, v131
	ds_read_b32 v80, v80
	v_subrev_u32_e32 v81, 48, v86
	v_min_u32_e32 v81, 0x3ff, v81
	v_lshl_add_u32 v81, v81, 2, v131
	ds_read_b32 v81, v81
	v_subrev_u32_e32 v82, 256, v86
	v_min_u32_e32 v82, 0x3ff, v82
	v_lshl_add_u32 v82, v82, 2, v131
	ds_read_b32 v82, v82
	v_subrev_u32_e32 v83, 272, v86
	v_min_u32_e32 v83, 0x3ff, v83
	v_lshl_add_u32 v83, v83, 2, v131
	ds_read_b32 v83, v83
	v_subrev_u32_e32 v84, 288, v86
	v_min_u32_e32 v84, 0x3ff, v84
	v_lshl_add_u32 v84, v84, 2, v131
	ds_read_b32 v84, v84
	v_subrev_u32_e32 v85, 304, v86
	v_min_u32_e32 v85, 0x3ff, v85
	v_lshl_add_u32 v85, v85, 2, v131
	ds_read_b32 v85, v85
	ds_read_b128 v[198:201], v192 offset:16384
	ds_read_b128 v[206:209], v192 offset:18688
	ds_read_b128 v[202:205], v192 offset:16448
	ds_read_b128 v[210:213], v192 offset:18752
	ds_read_b128 v[214:217], v192 offset:20992
	ds_read_b128 v[222:225], v192 offset:23296
	ds_read_b128 v[218:221], v192 offset:21056
	ds_read_b128 v[226:229], v192 offset:23360
	s_waitcnt lgkmcnt(6)
	v_mfma_f32_16x16x32_bf16 v[62:65], v[198:201], v[2:5], 0
	v_mfma_f32_16x16x32_bf16 v[66:69], v[206:209], v[2:5], 0
	s_waitcnt lgkmcnt(4)
	v_mfma_f32_16x16x32_bf16 v[62:65], v[202:205], v[6:9], v[62:65]
	v_mfma_f32_16x16x32_bf16 v[66:69], v[210:213], v[6:9], v[66:69]
	s_waitcnt lgkmcnt(2)
	v_mfma_f32_16x16x32_bf16 v[70:73], v[214:217], v[2:5], 0
	v_mfma_f32_16x16x32_bf16 v[74:77], v[222:225], v[2:5], 0
	s_waitcnt lgkmcnt(0)
	v_mfma_f32_16x16x32_bf16 v[70:73], v[218:221], v[6:9], v[70:73]
	v_mfma_f32_16x16x32_bf16 v[74:77], v[226:229], v[6:9], v[74:77]
	ds_read_b64_tr_b16 v[198:199], v193 offset:25600
	ds_read_b64_tr_b16 v[200:201], v193 offset:27904
	ds_read_b64_tr_b16 v[202:203], v193 offset:30208
	ds_read_b64_tr_b16 v[204:205], v193 offset:32512
	ds_read_b64_tr_b16 v[206:207], v193 offset:25632
	ds_read_b64_tr_b16 v[208:209], v193 offset:27936
	ds_read_b64_tr_b16 v[210:211], v193 offset:30240
	v_fmamk_f32 v62, v62, 0x3fb8aa3b, v78
	v_fmamk_f32 v63, v63, 0x3fb8aa3b, v79
	v_fmamk_f32 v64, v64, 0x3fb8aa3b, v80
	v_fmamk_f32 v65, v65, 0x3fb8aa3b, v81
	v_fmamk_f32 v66, v66, 0x3fb8aa3b, v82
	v_fmamk_f32 v67, v67, 0x3fb8aa3b, v83
	v_fmamk_f32 v68, v68, 0x3fb8aa3b, v84
	v_fmamk_f32 v69, v69, 0x3fb8aa3b, v85
	v_cmp_le_i32_e32 vcc, 0, v86
	s_nop 1
	v_cndmask_b32_e32 v62, v243, v62, vcc
	v_cmp_le_i32_e32 vcc, 16, v86
	s_nop 1
	v_cndmask_b32_e32 v63, v243, v63, vcc
	v_cmp_le_i32_e32 vcc, 32, v86
	s_nop 1
	v_cndmask_b32_e32 v64, v243, v64, vcc
	v_cmp_le_i32_e32 vcc, 48, v86
	s_nop 1
	v_cndmask_b32_e32 v65, v243, v65, vcc
	v_cmp_le_i32_e32 vcc, 256, v86
	s_nop 1
	v_cndmask_b32_e32 v66, v243, v66, vcc
	v_cmp_le_i32_e32 vcc, 272, v86
	s_nop 1
	v_cndmask_b32_e32 v67, v243, v67, vcc
	v_cmp_le_i32_e32 vcc, 288, v86
	s_nop 1
	v_cndmask_b32_e32 v68, v243, v68, vcc
	v_cmp_le_i32_e32 vcc, 304, v86
	s_nop 1
	v_cndmask_b32_e32 v69, v243, v69, vcc
	v_subrev_u32_e32 v78, 512, v86
	v_min_u32_e32 v78, 0x3ff, v78
	v_lshl_add_u32 v78, v78, 2, v131
	ds_read_b32 v78, v78
	v_subrev_u32_e32 v79, 528, v86
	v_min_u32_e32 v79, 0x3ff, v79
	v_lshl_add_u32 v79, v79, 2, v131
	ds_read_b32 v79, v79
	v_subrev_u32_e32 v80, 544, v86
	v_min_u32_e32 v80, 0x3ff, v80
	v_lshl_add_u32 v80, v80, 2, v131
	ds_read_b32 v80, v80
	v_subrev_u32_e32 v81, 560, v86
	v_min_u32_e32 v81, 0x3ff, v81
	v_lshl_add_u32 v81, v81, 2, v131
	ds_read_b32 v81, v81
	v_subrev_u32_e32 v82, 768, v86
	v_min_u32_e32 v82, 0x3ff, v82
	v_lshl_add_u32 v82, v82, 2, v131
	ds_read_b32 v82, v82
	v_subrev_u32_e32 v83, 784, v86
	v_min_u32_e32 v83, 0x3ff, v83
	v_lshl_add_u32 v83, v83, 2, v131
	ds_read_b32 v83, v83
	v_subrev_u32_e32 v84, 800, v86
	v_min_u32_e32 v84, 0x3ff, v84
	v_lshl_add_u32 v84, v84, 2, v131
	ds_read_b32 v84, v84
	v_subrev_u32_e32 v85, 816, v86
	v_min_u32_e32 v85, 0x3ff, v85
	v_lshl_add_u32 v85, v85, 2, v131
	ds_read_b32 v85, v85
	ds_read_b64_tr_b16 v[212:213], v193 offset:32544
	ds_read_b64_tr_b16 v[214:215], v193 offset:25664
	ds_read_b64_tr_b16 v[216:217], v193 offset:27968
	ds_read_b64_tr_b16 v[218:219], v193 offset:30272
	ds_read_b64_tr_b16 v[220:221], v193 offset:32576
	ds_read_b64_tr_b16 v[222:223], v193 offset:25696
	ds_read_b64_tr_b16 v[224:225], v193 offset:28000
	ds_read_b64_tr_b16 v[226:227], v193 offset:30304
	ds_read_b64_tr_b16 v[228:229], v193 offset:32608
	s_waitcnt lgkmcnt(9)
; #define LAS __attribute__((address_space(3)))
; template <int D, class SF>
; __device__ __forceinline__ void attn_step(const bf16x8 (&qf)[D / 32], const LAS bf16_t* Ks, const LAS bf16_t* Vt, f32x4 (&o)[D / 16], float& m, float& lsum, float& alpha_out, bf16x8& pf0_out, bf16x8& pf1_out, const int lane, SF sf) {
;     ...
;     float mx = fmaxf(fmaxf(fmaxf(v[0], v[1]), fmaxf(v[2], v[3])), fmaxf(fmaxf(v[4], v[5]), fmaxf(v[6], v[7])));
;     mx = fmaxf(mx, fmaxf(fmaxf(fmaxf(v[8], v[9]), fmaxf(v[10], v[11])), fmaxf(fmaxf(v[12], v[13]), fmaxf(v[14], v[15]))));
;     mx = rows_max(mx);
;     const float mnew = fmaxf(m, mx);
;     const float mc = fmaxf(mnew, -1e20f);
;     const float alpha = __builtin_amdgcn_exp2f(fmaxf(m, -1e20f) - mc);
;     float p[16], rs = 0.f;
; #pragma unroll
;     for (int r = 0; r < 16; ++r) { p[r] = __builtin_amdgcn_exp2f(v[r] - mc); rs += p[r]; }
;     rs = rows_sum(rs);
;     lsum = lsum * alpha + rs; m = mnew;
;     union { u32x4 u; bf16x8 b; } pk0, pk1;
;     pk0.u.x = cvt_pk_bf16(p[0], p[1]); pk0.u.y = cvt_pk_bf16(p[2], p[3]); pk0.u.z = cvt_pk_bf16(p[4], p[5]); pk0.u.w = cvt_pk_bf16(p[6], p[7]);
;     pk1.u.x = cvt_pk_bf16(p[8], p[9]); pk1.u.y = cvt_pk_bf16(p[10], p[11]); pk1.u.z = cvt_pk_bf16(p[12], p[13]); pk1.u.w = cvt_pk_bf16(p[14], p[15]);
;     if (__builtin_amdgcn_ballot_w64(alpha != 1.0f) != 0ull) {
; #pragma unroll
;         for (int dt = 0; dt < D / 16; ++dt) o[dt] *= alpha;
;     }
; #pragma unroll
;     for (int dt = 0; dt < D / 16; ++dt) {
;         const LAS bf16_t* vp = Vt + (16 * dt + c) * 72 + 4 * i;
;         union { u32x4 u; bf16x8 b; } vf0, vf1; const u32x2 a0 = *(const LAS u32x2*)vp, a1 = *(const LAS u32x2*)(vp + 16), b0 = *(const LAS u32x2*)(vp + 32), b1 = *(const LAS u32x2*)(vp + 48);
;         vf0.u.x = a0.x; vf0.u.y = a0.y; vf0.u.z = a1.x; vf0.u.w = a1.y; vf1.u.x = b0.x; vf1.u.y = b0.y; vf1.u.z = b1.x; vf1.u.w = b1.y;
;         o[dt] = mfma16(vf0.b, pk0.b, o[dt]); o[dt] = mfma16(vf1.b, pk1.b, o[dt]);
;     }
; __device__ __forceinline__ void nsa_unit(LAS unsigned char* lds, const Ctx& P, int l, int b, int hkv, int tb) {
;     ...
; #pragma unroll
;                 for (int jt = 0; jt < 4; ++jt) oi[jt] *= alpha;
;                 oi[kt] = mfma16(ovA[0], pf, oi[kt]); oi[kt] = mfma16(ovA[1], pf1, oi[kt]);
	v_fmamk_f32 v70, v70, 0x3fb8aa3b, v78
	v_fmamk_f32 v71, v71, 0x3fb8aa3b, v79
	v_fmamk_f32 v72, v72, 0x3fb8aa3b, v80
	v_fmamk_f32 v73, v73, 0x3fb8aa3b, v81
	v_fmamk_f32 v74, v74, 0x3fb8aa3b, v82
	v_fmamk_f32 v75, v75, 0x3fb8aa3b, v83
	v_fmamk_f32 v76, v76, 0x3fb8aa3b, v84
	v_fmamk_f32 v77, v77, 0x3fb8aa3b, v85
	v_cmp_le_i32_e32 vcc, 512, v86
	s_nop 1
	v_cndmask_b32_e32 v70, v243, v70, vcc
	v_cmp_le_i32_e32 vcc, 528, v86
	s_nop 1
	v_cndmask_b32_e32 v71, v243, v71, vcc
	v_cmp_le_i32_e32 vcc, 544, v86
	s_nop 1
	v_cndmask_b32_e32 v72, v243, v72, vcc
	v_cmp_le_i32_e32 vcc, 560, v86
	s_nop 1
	v_cndmask_b32_e32 v73, v243, v73, vcc
	v_cmp_le_i32_e32 vcc, 768, v86
	s_nop 1
	v_cndmask_b32_e32 v74, v243, v74, vcc
	v_cmp_le_i32_e32 vcc, 784, v86
	s_nop 1
	v_cndmask_b32_e32 v75, v243, v75, vcc
	v_cmp_le_i32_e32 vcc, 800, v86
	s_nop 1
	v_cndmask_b32_e32 v76, v243, v76, vcc
	v_cmp_le_i32_e32 vcc, 816, v86
	s_nop 1
	v_cndmask_b32_e32 v77, v243, v77, vcc
	v_max3_f32 v92, v62, v63, v64
	v_max3_f32 v87, v65, v66, v67
	v_max3_f32 v88, v68, v69, v70
	v_max3_f32 v89, v71, v72, v73
	v_max3_f32 v91, v74, v75, v76
	v_max3_f32 v92, v92, v87, v77
	v_max3_f32 v88, v88, v89, v91
	v_max_f32_e32 v92, v92, v88
	v_mov_b32_e32 v87, v92
	s_nop 1
	v_permlane16_swap_b32_e32 v92, v87
	v_max_f32_e32 v92, v92, v87
	v_mov_b32_e32 v87, v92
	s_nop 1
	v_permlane32_swap_b32_e32 v92, v87
	v_max_f32_e32 v92, v92, v87
	v_max_f32_e32 v88, v137, v92
	v_max_f32_e32 v90, 0xe0ad78ec, v137
	v_max_f32_e32 v89, 0xe0ad78ec, v88
	v_sub_f32_e32 v90, v90, v89
	v_mov_b32_e32 v137, v88
	v_exp_f32_e32 v90, v90
	v_sub_f32_e32 v62, v62, v89
	v_sub_f32_e32 v63, v63, v89
	v_sub_f32_e32 v64, v64, v89
	v_sub_f32_e32 v65, v65, v89
	v_exp_f32_e32 v62, v62
	v_exp_f32_e32 v63, v63
	v_exp_f32_e32 v64, v64
	v_exp_f32_e32 v65, v65
	v_sub_f32_e32 v66, v66, v89
	v_sub_f32_e32 v67, v67, v89
	v_sub_f32_e32 v68, v68, v89
	v_sub_f32_e32 v69, v69, v89
	v_exp_f32_e32 v66, v66
	v_exp_f32_e32 v67, v67
	v_exp_f32_e32 v68, v68
	v_exp_f32_e32 v69, v69
	v_sub_f32_e32 v70, v70, v89
	v_sub_f32_e32 v71, v71, v89
	v_sub_f32_e32 v72, v72, v89
	v_sub_f32_e32 v73, v73, v89
	v_exp_f32_e32 v70, v70
	v_exp_f32_e32 v71, v71
	v_exp_f32_e32 v72, v72
	v_exp_f32_e32 v73, v73
	v_sub_f32_e32 v74, v74, v89
	v_sub_f32_e32 v75, v75, v89
	v_sub_f32_e32 v76, v76, v89
	v_sub_f32_e32 v77, v77, v89
	v_exp_f32_e32 v74, v74
	v_exp_f32_e32 v75, v75
	v_exp_f32_e32 v76, v76
	v_exp_f32_e32 v77, v77
	s_nop 0
	v_add_f32_e32 v86, v62, v63
	v_add_f32_e32 v87, v64, v65
	v_add_f32_e32 v88, v66, v67
	v_add_f32_e32 v89, v68, v69
	v_add_f32_e32 v86, v86, v70
	v_add_f32_e32 v87, v87, v71
	v_add_f32_e32 v88, v88, v72
	v_add_f32_e32 v89, v89, v73
	v_add_f32_e32 v86, v86, v74
	v_add_f32_e32 v87, v87, v75
	v_add_f32_e32 v88, v88, v76
	v_add_f32_e32 v89, v89, v77
	v_add_f32_e32 v86, v86, v87
	v_add_f32_e32 v88, v88, v89
	v_add_f32_e32 v86, v86, v88
	v_cvt_pk_bf16_f32 v78, v62, v63
	v_cvt_pk_bf16_f32 v79, v64, v65
	v_cvt_pk_bf16_f32 v80, v66, v67
	v_cvt_pk_bf16_f32 v81, v68, v69
	v_cvt_pk_bf16_f32 v82, v70, v71
	v_cvt_pk_bf16_f32 v83, v72, v73
	v_cvt_pk_bf16_f32 v84, v74, v75
	v_cvt_pk_bf16_f32 v85, v76, v77
	v_mov_b32_e32 v87, v86
	s_nop 1
	v_permlane16_swap_b32_e32 v86, v87
	v_add_f32_e32 v86, v86, v87
	v_mov_b32_e32 v87, v86
	s_nop 1
	v_permlane32_swap_b32_e32 v86, v87
	v_add_f32_e32 v86, v86, v87
	v_fma_f32 v138, v138, v90, v86
	v_cmp_neq_f32_e64 s[0:1], 1.0, v90
	s_cmp_eq_u64 s[0:1], 0
	s_cbranch_scc1 .Lcm_nosc_4
	v_pk_mul_f32 v[30:31], v[30:31], v[90:91] op_sel_hi:[1,0]
	v_pk_mul_f32 v[32:33], v[32:33], v[90:91] op_sel_hi:[1,0]
	v_pk_mul_f32 v[34:35], v[34:35], v[90:91] op_sel_hi:[1,0]
	v_pk_mul_f32 v[36:37], v[36:37], v[90:91] op_sel_hi:[1,0]
	v_pk_mul_f32 v[38:39], v[38:39], v[90:91] op_sel_hi:[1,0]
	v_pk_mul_f32 v[40:41], v[40:41], v[90:91] op_sel_hi:[1,0]
	v_pk_mul_f32 v[42:43], v[42:43], v[90:91] op_sel_hi:[1,0]
	v_pk_mul_f32 v[44:45], v[44:45], v[90:91] op_sel_hi:[1,0]
	v_pk_mul_f32 v[46:47], v[46:47], v[90:91] op_sel_hi:[1,0]
	v_pk_mul_f32 v[48:49], v[48:49], v[90:91] op_sel_hi:[1,0]
	v_pk_mul_f32 v[50:51], v[50:51], v[90:91] op_sel_hi:[1,0]
	v_pk_mul_f32 v[52:53], v[52:53], v[90:91] op_sel_hi:[1,0]
	v_pk_mul_f32 v[54:55], v[54:55], v[90:91] op_sel_hi:[1,0]
	v_pk_mul_f32 v[56:57], v[56:57], v[90:91] op_sel_hi:[1,0]
	v_pk_mul_f32 v[58:59], v[58:59], v[90:91] op_sel_hi:[1,0]
	v_pk_mul_f32 v[60:61], v[60:61], v[90:91] op_sel_hi:[1,0]
.Lcm_nosc_4:
	s_waitcnt lgkmcnt(0)
	s_nop 1
	v_mfma_f32_16x16x32_bf16 v[30:33], v[198:201], v[78:81], v[30:33]
	v_mfma_f32_16x16x32_bf16 v[34:37], v[206:209], v[78:81], v[34:37]
	v_mfma_f32_16x16x32_bf16 v[38:41], v[214:217], v[78:81], v[38:41]
	v_mfma_f32_16x16x32_bf16 v[42:45], v[222:225], v[78:81], v[42:45]
	v_mfma_f32_16x16x32_bf16 v[30:33], v[202:205], v[82:85], v[30:33]
	v_mfma_f32_16x16x32_bf16 v[34:37], v[210:213], v[82:85], v[34:37]
	v_mfma_f32_16x16x32_bf16 v[38:41], v[218:221], v[82:85], v[38:41]
	v_mfma_f32_16x16x32_bf16 v[42:45], v[226:229], v[82:85], v[42:45]
	v_mfma_f32_16x16x32_bf16 v[46:49], v[160:163], v[78:81], v[46:49]
	s_cmp_eq_u32 s4, 3
	s_cbranch_scc1 .Lcm_nob_5
	v_mfma_f32_16x16x32_bf16 v[50:53], v[230:233], v[82:85], v[50:53]
; #define LAS __attribute__((address_space(3)))
; __device__ __forceinline__ f32x4 mfma16(bf16x8 a, bf16x8 b, f32x4 c) { return __builtin_amdgcn_mfma_f32_16x16x32_bf16(a, b, c, 0, 0, 0); }
; template <int D, class SF>
; __device__ __forceinline__ void attn_step(const bf16x8 (&qf)[D / 32], const LAS bf16_t* Ks, const LAS bf16_t* Vt, f32x4 (&o)[D / 16], float& m, float& lsum, float& alpha_out, bf16x8& pf0_out, bf16x8& pf1_out, const int lane, SF sf) {
;     ...
;     for (int ks = 0; ks < D / 32; ++ks) {
; #pragma unroll
;         for (int t = 0; t < 4; ++t) { const bf16x8 kf = *(const LAS bf16x8*)(Ks + (16 * t + c) * KSTR + ks * 32 + 8 * i); s[t] = mfma16(kf, qf[ks], s[t]); }
;     }
;     float v[16];
; #pragma unroll
;     for (int t = 0; t < 4; ++t)
; #pragma unroll
;         for (int r = 0; r < 4; ++r) v[4 * t + r] = sf(16 * t + 4 * i + r, s[t][r]);
; __device__ __forceinline__ void nsa_unit(LAS unsigned char* lds, const Ctx& P, int l, int b, int hkv, int tb) {
;     ...
;             for (int sl = 0; sl < 2; ++sl) if (sl == 0 || hasb) {
;                 const int kt = 2 * pr + sl; const LAS bf16_t* Ks = KV + sl * 9216; const LAS bf16_t* Vt = Ks + 4608; const int nb = kt * 64;
;                 attn_step<64>(qs, Ks, Vt, o, m, lsum, alpha, pf, pf1, lane,
;                     [&](int kk, float s) { const int dist = tqs - (16 * (nb + kk) + 31); return dist >= 0 ? s * LOG2E + lut[min((unsigned)dist, 1023u)] : NEGBIG; });
.Lcm_nob_5:
	v_mfma_f32_16x16x32_bf16 v[46:49], v[170:173], v[82:85], v[46:49]
	v_lshlrev_b32_e32 v86, 6, v103
	v_sub_u32_e32 v86, v98, v86
	v_subrev_u32_e32 v86, s5, v86
	v_subrev_u32_e32 v78, 0, v86
	v_min_u32_e32 v78, 0x3ff, v78
	v_lshl_add_u32 v78, v78, 2, v131
	ds_read_b32 v78, v78
	v_subrev_u32_e32 v79, 16, v86
	v_min_u32_e32 v79, 0x3ff, v79
	v_lshl_add_u32 v79, v79, 2, v131
	ds_read_b32 v79, v79
	v_subrev_u32_e32 v80, 32, v86
	v_min_u32_e32 v80, 0x3ff, v80
	v_lshl_add_u32 v80, v80, 2, v131
	ds_read_b32 v80, v80
	v_subrev_u32_e32 v81, 48, v86
	v_min_u32_e32 v81, 0x3ff, v81
	v_lshl_add_u32 v81, v81, 2, v131
	ds_read_b32 v81, v81
	v_subrev_u32_e32 v82, 256, v86
	v_min_u32_e32 v82, 0x3ff, v82
	v_lshl_add_u32 v82, v82, 2, v131
	ds_read_b32 v82, v82
	v_subrev_u32_e32 v83, 272, v86
	v_min_u32_e32 v83, 0x3ff, v83
	v_lshl_add_u32 v83, v83, 2, v131
	ds_read_b32 v83, v83
	v_subrev_u32_e32 v84, 288, v86
	v_min_u32_e32 v84, 0x3ff, v84
	v_lshl_add_u32 v84, v84, 2, v131
	ds_read_b32 v84, v84
	v_subrev_u32_e32 v85, 304, v86
	v_min_u32_e32 v85, 0x3ff, v85
	v_lshl_add_u32 v85, v85, 2, v131
	ds_read_b32 v85, v85
	ds_read_b128 v[198:201], v192 offset:16384
	ds_read_b128 v[206:209], v192 offset:18688
	ds_read_b128 v[202:205], v192 offset:16448
	ds_read_b128 v[210:213], v192 offset:18752
	ds_read_b128 v[214:217], v192 offset:20992
	ds_read_b128 v[222:225], v192 offset:23296
	ds_read_b128 v[218:221], v192 offset:21056
	ds_read_b128 v[226:229], v192 offset:23360
	s_waitcnt lgkmcnt(6)
	v_mfma_f32_16x16x32_bf16 v[62:65], v[198:201], v[10:13], 0
	v_mfma_f32_16x16x32_bf16 v[66:69], v[206:209], v[10:13], 0
	s_waitcnt lgkmcnt(4)
	v_mfma_f32_16x16x32_bf16 v[62:65], v[202:205], v[14:17], v[62:65]
	v_mfma_f32_16x16x32_bf16 v[66:69], v[210:213], v[14:17], v[66:69]
	s_waitcnt lgkmcnt(2)
	v_mfma_f32_16x16x32_bf16 v[70:73], v[214:217], v[10:13], 0
	v_mfma_f32_16x16x32_bf16 v[74:77], v[222:225], v[10:13], 0
	s_waitcnt lgkmcnt(0)
	v_mfma_f32_16x16x32_bf16 v[70:73], v[218:221], v[14:17], v[70:73]
	v_mfma_f32_16x16x32_bf16 v[74:77], v[226:229], v[14:17], v[74:77]
	ds_read_b64_tr_b16 v[198:199], v193 offset:25600
	ds_read_b64_tr_b16 v[200:201], v193 offset:27904
	ds_read_b64_tr_b16 v[202:203], v193 offset:30208
	ds_read_b64_tr_b16 v[204:205], v193 offset:32512
	ds_read_b64_tr_b16 v[206:207], v193 offset:25632
	ds_read_b64_tr_b16 v[208:209], v193 offset:27936
	ds_read_b64_tr_b16 v[210:211], v193 offset:30240
	v_fmamk_f32 v62, v62, 0x3fb8aa3b, v78
	v_fmamk_f32 v63, v63, 0x3fb8aa3b, v79
	v_fmamk_f32 v64, v64, 0x3fb8aa3b, v80
	v_fmamk_f32 v65, v65, 0x3fb8aa3b, v81
	v_fmamk_f32 v66, v66, 0x3fb8aa3b, v82
	v_fmamk_f32 v67, v67, 0x3fb8aa3b, v83
	v_fmamk_f32 v68, v68, 0x3fb8aa3b, v84
	v_fmamk_f32 v69, v69, 0x3fb8aa3b, v85
	v_cmp_le_i32_e32 vcc, 0, v86
	s_nop 1
	v_cndmask_b32_e32 v62, v243, v62, vcc
	v_cmp_le_i32_e32 vcc, 16, v86
	s_nop 1
	v_cndmask_b32_e32 v63, v243, v63, vcc
	v_cmp_le_i32_e32 vcc, 32, v86
	s_nop 1
	v_cndmask_b32_e32 v64, v243, v64, vcc
	v_cmp_le_i32_e32 vcc, 48, v86
	s_nop 1
	v_cndmask_b32_e32 v65, v243, v65, vcc
	v_cmp_le_i32_e32 vcc, 256, v86
	s_nop 1
	v_cndmask_b32_e32 v66, v243, v66, vcc
	v_cmp_le_i32_e32 vcc, 272, v86
	s_nop 1
	v_cndmask_b32_e32 v67, v243, v67, vcc
	v_cmp_le_i32_e32 vcc, 288, v86
	s_nop 1
	v_cndmask_b32_e32 v68, v243, v68, vcc
	v_cmp_le_i32_e32 vcc, 304, v86
	s_nop 1
	v_cndmask_b32_e32 v69, v243, v69, vcc
	v_subrev_u32_e32 v78, 512, v86
	v_min_u32_e32 v78, 0x3ff, v78
	v_lshl_add_u32 v78, v78, 2, v131
	ds_read_b32 v78, v78
	v_subrev_u32_e32 v79, 528, v86
	v_min_u32_e32 v79, 0x3ff, v79
	v_lshl_add_u32 v79, v79, 2, v131
	ds_read_b32 v79, v79
	v_subrev_u32_e32 v80, 544, v86
	v_min_u32_e32 v80, 0x3ff, v80
	v_lshl_add_u32 v80, v80, 2, v131
	ds_read_b32 v80, v80
	v_subrev_u32_e32 v81, 560, v86
	v_min_u32_e32 v81, 0x3ff, v81
	v_lshl_add_u32 v81, v81, 2, v131
	ds_read_b32 v81, v81
	v_subrev_u32_e32 v82, 768, v86
	v_min_u32_e32 v82, 0x3ff, v82
	v_lshl_add_u32 v82, v82, 2, v131
	ds_read_b32 v82, v82
	v_subrev_u32_e32 v83, 784, v86
	v_min_u32_e32 v83, 0x3ff, v83
	v_lshl_add_u32 v83, v83, 2, v131
	ds_read_b32 v83, v83
	v_subrev_u32_e32 v84, 800, v86
	v_min_u32_e32 v84, 0x3ff, v84
	v_lshl_add_u32 v84, v84, 2, v131
	ds_read_b32 v84, v84
	v_subrev_u32_e32 v85, 816, v86
	v_min_u32_e32 v85, 0x3ff, v85
	v_lshl_add_u32 v85, v85, 2, v131
	ds_read_b32 v85, v85
	ds_read_b64_tr_b16 v[212:213], v193 offset:32544
	ds_read_b64_tr_b16 v[214:215], v193 offset:25664
	ds_read_b64_tr_b16 v[216:217], v193 offset:27968
	ds_read_b64_tr_b16 v[218:219], v193 offset:30272
	ds_read_b64_tr_b16 v[220:221], v193 offset:32576
	ds_read_b64_tr_b16 v[222:223], v193 offset:25696
	ds_read_b64_tr_b16 v[224:225], v193 offset:28000
	ds_read_b64_tr_b16 v[226:227], v193 offset:30304
	ds_read_b64_tr_b16 v[228:229], v193 offset:32608
	s_waitcnt lgkmcnt(9)
; #define LAS __attribute__((address_space(3)))
; template <int D, class SF>
; __device__ __forceinline__ void attn_step(const bf16x8 (&qf)[D / 32], const LAS bf16_t* Ks, const LAS bf16_t* Vt, f32x4 (&o)[D / 16], float& m, float& lsum, float& alpha_out, bf16x8& pf0_out, bf16x8& pf1_out, const int lane, SF sf) {
;     ...
;     float mx = fmaxf(fmaxf(fmaxf(v[0], v[1]), fmaxf(v[2], v[3])), fmaxf(fmaxf(v[4], v[5]), fmaxf(v[6], v[7])));
;     mx = fmaxf(mx, fmaxf(fmaxf(fmaxf(v[8], v[9]), fmaxf(v[10], v[11])), fmaxf(fmaxf(v[12], v[13]), fmaxf(v[14], v[15]))));
;     mx = rows_max(mx);
;     const float mnew = fmaxf(m, mx);
;     const float mc = fmaxf(mnew, -1e20f);
;     const float alpha = __builtin_amdgcn_exp2f(fmaxf(m, -1e20f) - mc);
;     float p[16], rs = 0.f;
; #pragma unroll
;     for (int r = 0; r < 16; ++r) { p[r] = __builtin_amdgcn_exp2f(v[r] - mc); rs += p[r]; }
;     rs = rows_sum(rs);
;     lsum = lsum * alpha + rs; m = mnew;
;     union { u32x4 u; bf16x8 b; } pk0, pk1;
;     pk0.u.x = cvt_pk_bf16(p[0], p[1]); pk0.u.y = cvt_pk_bf16(p[2], p[3]); pk0.u.z = cvt_pk_bf16(p[4], p[5]); pk0.u.w = cvt_pk_bf16(p[6], p[7]);
;     pk1.u.x = cvt_pk_bf16(p[8], p[9]); pk1.u.y = cvt_pk_bf16(p[10], p[11]); pk1.u.z = cvt_pk_bf16(p[12], p[13]); pk1.u.w = cvt_pk_bf16(p[14], p[15]);
;     if (__builtin_amdgcn_ballot_w64(alpha != 1.0f) != 0ull) {
; #pragma unroll
;         for (int dt = 0; dt < D / 16; ++dt) o[dt] *= alpha;
;     }
; #pragma unroll
;     for (int dt = 0; dt < D / 16; ++dt) {
;         const LAS bf16_t* vp = Vt + (16 * dt + c) * 72 + 4 * i;
;         union { u32x4 u; bf16x8 b; } vf0, vf1; const u32x2 a0 = *(const LAS u32x2*)vp, a1 = *(const LAS u32x2*)(vp + 16), b0 = *(const LAS u32x2*)(vp + 32), b1 = *(const LAS u32x2*)(vp + 48);
;         vf0.u.x = a0.x; vf0.u.y = a0.y; vf0.u.z = a1.x; vf0.u.w = a1.y; vf1.u.x = b0.x; vf1.u.y = b0.y; vf1.u.z = b1.x; vf1.u.w = b1.y;
;         o[dt] = mfma16(vf0.b, pk0.b, o[dt]); o[dt] = mfma16(vf1.b, pk1.b, o[dt]);
;     }
; __device__ __forceinline__ void nsa_unit(LAS unsigned char* lds, const Ctx& P, int l, int b, int hkv, int tb) {
;     ...
; #pragma unroll
;                 for (int jt = 0; jt < 4; ++jt) oi[jt] *= alpha;
;                 oi[kt] = mfma16(ovA[0], pf, oi[kt]); oi[kt] = mfma16(ovA[1], pf1, oi[kt]);
	v_fmamk_f32 v70, v70, 0x3fb8aa3b, v78
	v_fmamk_f32 v71, v71, 0x3fb8aa3b, v79
	v_fmamk_f32 v72, v72, 0x3fb8aa3b, v80
	v_fmamk_f32 v73, v73, 0x3fb8aa3b, v81
	v_fmamk_f32 v74, v74, 0x3fb8aa3b, v82
	v_fmamk_f32 v75, v75, 0x3fb8aa3b, v83
	v_fmamk_f32 v76, v76, 0x3fb8aa3b, v84
	v_fmamk_f32 v77, v77, 0x3fb8aa3b, v85
	v_cmp_le_i32_e32 vcc, 512, v86
	s_nop 1
	v_cndmask_b32_e32 v70, v243, v70, vcc
	v_cmp_le_i32_e32 vcc, 528, v86
	s_nop 1
	v_cndmask_b32_e32 v71, v243, v71, vcc
	v_cmp_le_i32_e32 vcc, 544, v86
	s_nop 1
	v_cndmask_b32_e32 v72, v243, v72, vcc
	v_cmp_le_i32_e32 vcc, 560, v86
	s_nop 1
	v_cndmask_b32_e32 v73, v243, v73, vcc
	v_cmp_le_i32_e32 vcc, 768, v86
	s_nop 1
	v_cndmask_b32_e32 v74, v243, v74, vcc
	v_cmp_le_i32_e32 vcc, 784, v86
	s_nop 1
	v_cndmask_b32_e32 v75, v243, v75, vcc
	v_cmp_le_i32_e32 vcc, 800, v86
	s_nop 1
	v_cndmask_b32_e32 v76, v243, v76, vcc
	v_cmp_le_i32_e32 vcc, 816, v86
	s_nop 1
	v_cndmask_b32_e32 v77, v243, v77, vcc
	v_max3_f32 v92, v62, v63, v64
	v_max3_f32 v87, v65, v66, v67
	v_max3_f32 v88, v68, v69, v70
	v_max3_f32 v89, v71, v72, v73
	v_max3_f32 v91, v74, v75, v76
	v_max3_f32 v92, v92, v87, v77
	v_max3_f32 v88, v88, v89, v91
	v_max_f32_e32 v92, v92, v88
	v_mov_b32_e32 v87, v92
	s_nop 1
	v_permlane16_swap_b32_e32 v92, v87
	v_max_f32_e32 v92, v92, v87
	v_mov_b32_e32 v87, v92
	s_nop 1
	v_permlane32_swap_b32_e32 v92, v87
	v_max_f32_e32 v92, v92, v87
	v_max_f32_e32 v88, v195, v92
	v_max_f32_e32 v90, 0xe0ad78ec, v195
	v_max_f32_e32 v89, 0xe0ad78ec, v88
	v_sub_f32_e32 v90, v90, v89
	v_mov_b32_e32 v195, v88
	v_exp_f32_e32 v90, v90
	v_sub_f32_e32 v62, v62, v89
	v_sub_f32_e32 v63, v63, v89
	v_sub_f32_e32 v64, v64, v89
	v_sub_f32_e32 v65, v65, v89
	v_exp_f32_e32 v62, v62
	v_exp_f32_e32 v63, v63
	v_exp_f32_e32 v64, v64
	v_exp_f32_e32 v65, v65
	v_sub_f32_e32 v66, v66, v89
	v_sub_f32_e32 v67, v67, v89
	v_sub_f32_e32 v68, v68, v89
	v_sub_f32_e32 v69, v69, v89
	v_exp_f32_e32 v66, v66
	v_exp_f32_e32 v67, v67
	v_exp_f32_e32 v68, v68
	v_exp_f32_e32 v69, v69
	v_sub_f32_e32 v70, v70, v89
	v_sub_f32_e32 v71, v71, v89
	v_sub_f32_e32 v72, v72, v89
	v_sub_f32_e32 v73, v73, v89
	v_exp_f32_e32 v70, v70
	v_exp_f32_e32 v71, v71
	v_exp_f32_e32 v72, v72
	v_exp_f32_e32 v73, v73
	v_sub_f32_e32 v74, v74, v89
	v_sub_f32_e32 v75, v75, v89
	v_sub_f32_e32 v76, v76, v89
	v_sub_f32_e32 v77, v77, v89
	v_exp_f32_e32 v74, v74
	v_exp_f32_e32 v75, v75
	v_exp_f32_e32 v76, v76
	v_exp_f32_e32 v77, v77
	s_nop 0
	v_add_f32_e32 v86, v62, v63
	v_add_f32_e32 v87, v64, v65
	v_add_f32_e32 v88, v66, v67
	v_add_f32_e32 v89, v68, v69
	v_add_f32_e32 v86, v86, v70
	v_add_f32_e32 v87, v87, v71
	v_add_f32_e32 v88, v88, v72
	v_add_f32_e32 v89, v89, v73
	v_add_f32_e32 v86, v86, v74
	v_add_f32_e32 v87, v87, v75
	v_add_f32_e32 v88, v88, v76
	v_add_f32_e32 v89, v89, v77
	v_add_f32_e32 v86, v86, v87
	v_add_f32_e32 v88, v88, v89
	v_add_f32_e32 v86, v86, v88
	v_cvt_pk_bf16_f32 v78, v62, v63
	v_cvt_pk_bf16_f32 v79, v64, v65
	v_cvt_pk_bf16_f32 v80, v66, v67
	v_cvt_pk_bf16_f32 v81, v68, v69
	v_cvt_pk_bf16_f32 v82, v70, v71
	v_cvt_pk_bf16_f32 v83, v72, v73
	v_cvt_pk_bf16_f32 v84, v74, v75
	v_cvt_pk_bf16_f32 v85, v76, v77
	v_mov_b32_e32 v87, v86
	s_nop 1
	v_permlane16_swap_b32_e32 v86, v87
	v_add_f32_e32 v86, v86, v87
	v_mov_b32_e32 v87, v86
	s_nop 1
	v_permlane32_swap_b32_e32 v86, v87
	v_add_f32_e32 v86, v86, v87
	v_fma_f32 v196, v196, v90, v86
	v_cmp_neq_f32_e64 s[0:1], 1.0, v90
	s_cmp_eq_u64 s[0:1], 0
	s_cbranch_scc1 .Lcm_nosc_6
	v_pk_mul_f32 v[174:175], v[174:175], v[90:91] op_sel_hi:[1,0]
	v_pk_mul_f32 v[176:177], v[176:177], v[90:91] op_sel_hi:[1,0]
	v_pk_mul_f32 v[178:179], v[178:179], v[90:91] op_sel_hi:[1,0]
	v_pk_mul_f32 v[180:181], v[180:181], v[90:91] op_sel_hi:[1,0]
	v_pk_mul_f32 v[182:183], v[182:183], v[90:91] op_sel_hi:[1,0]
	v_pk_mul_f32 v[184:185], v[184:185], v[90:91] op_sel_hi:[1,0]
	v_pk_mul_f32 v[186:187], v[186:187], v[90:91] op_sel_hi:[1,0]
	v_pk_mul_f32 v[188:189], v[188:189], v[90:91] op_sel_hi:[1,0]
	v_pk_mul_f32 v[18:19], v[18:19], v[90:91] op_sel_hi:[1,0]
	v_pk_mul_f32 v[20:21], v[20:21], v[90:91] op_sel_hi:[1,0]
	v_pk_mul_f32 v[22:23], v[22:23], v[90:91] op_sel_hi:[1,0]
	v_pk_mul_f32 v[24:25], v[24:25], v[90:91] op_sel_hi:[1,0]
	v_pk_mul_f32 v[26:27], v[26:27], v[90:91] op_sel_hi:[1,0]
	v_pk_mul_f32 v[28:29], v[28:29], v[90:91] op_sel_hi:[1,0]
	v_pk_mul_f32 v[104:105], v[104:105], v[90:91] op_sel_hi:[1,0]
	v_pk_mul_f32 v[106:107], v[106:107], v[90:91] op_sel_hi:[1,0]
.Lcm_nosc_6:
	s_waitcnt lgkmcnt(0)
	s_nop 1
	v_mfma_f32_16x16x32_bf16 v[174:177], v[198:201], v[78:81], v[174:177]
	v_mfma_f32_16x16x32_bf16 v[178:181], v[206:209], v[78:81], v[178:181]
	v_mfma_f32_16x16x32_bf16 v[182:185], v[214:217], v[78:81], v[182:185]
	v_mfma_f32_16x16x32_bf16 v[186:189], v[222:225], v[78:81], v[186:189]
	v_mfma_f32_16x16x32_bf16 v[174:177], v[202:205], v[82:85], v[174:177]
	v_mfma_f32_16x16x32_bf16 v[178:181], v[210:213], v[82:85], v[178:181]
	v_mfma_f32_16x16x32_bf16 v[182:185], v[218:221], v[82:85], v[182:185]
	v_mfma_f32_16x16x32_bf16 v[186:189], v[226:229], v[82:85], v[186:189]
	v_mfma_f32_16x16x32_bf16 v[18:21], v[160:163], v[78:81], v[18:21]
	s_cmp_eq_u32 s4, 3
	s_cbranch_scc1 .Lcm_nob_7
	v_mfma_f32_16x16x32_bf16 v[22:25], v[230:233], v[82:85], v[22:25]
; #define LAS __attribute__((address_space(3)))
; __device__ __forceinline__ float bf2f(bf16_t v) { return __uint_as_float(((unsigned)v) << 16); }
; __device__ __forceinline__ float sigmoidf_(float x) { return __builtin_amdgcn_rcpf(1.0f + __expf(-x)); }
; __device__ __forceinline__ f32x4 mfma16(bf16x8 a, bf16x8 b, f32x4 c) { return __builtin_amdgcn_mfma_f32_16x16x32_bf16(a, b, c, 0, 0, 0); }
; __device__ __forceinline__ void nsa_unit(LAS unsigned char* lds, const Ctx& P, int l, int b, int hkv, int tb) {
;     ...
;         for (int pr = 0; pr < 2; ++pr) if (2 * pr < ntile) {
;             const bool hasb = 2 * pr + 1 < ntile;
;             __syncthreads();
;             load2(KC, VC, 64, 128 * pr, 128 * pr + 64, hasb, 255);
;             __syncthreads();
; #pragma unroll
;             for (int sl = 0; sl < 2; ++sl) if (sl == 0 || hasb) {
;                 const int kt = 2 * pr + sl; const LAS bf16_t* Ks = KV + sl * 9216; const LAS bf16_t* Vt = Ks + 4608; const int nb = kt * 64;
;                 attn_step<64>(qs, Ks, Vt, o, m, lsum, alpha, pf, pf1, lane,
;                     [&](int kk, float s) { const int dist = tqs - (16 * (nb + kk) + 31); return dist >= 0 ? s * LOG2E + lut[min((unsigned)dist, 1023u)] : NEGBIG; });
; #pragma unroll
;                 for (int jt = 0; jt < 4; ++jt) oi[jt] *= alpha;
;                 oi[kt] = mfma16(ovA[0], pf, oi[kt]); oi[kt] = mfma16(ovA[1], pf1, oi[kt]);
;                 if (kt + 1 < 4) { oi[kt + 1 < 4 ? kt + 1 : 3] = mfma16(ovB[0], pf, oi[kt + 1 < 4 ? kt + 1 : 3]); oi[kt + 1 < 4 ? kt + 1 : 3] = mfma16(ovB[1], pf1, oi[kt + 1 < 4 ? kt + 1 : 3]); }
;             }
;         }
;         const float inv = 1.0f / fmaxf(lsum, 1e-30f);
;         const float g0 = sigmoidf_(bf2f(H[((size_t)b * SEQ + tqs) * LDH + C_GL + hq]) + P.in[21][l * 48 + hq]) * inv;
; #pragma unroll
;         for (int dt = 0; dt < 4; ++dt) { park[(sb * 4 + dt) * 64] = o[dt] * g0;
;             *(LAS f32x4*)(impb + (g * 64 + 32 * th + 16 * sb + c) * 64 + 16 * dt + 4 * i) = oi[dt] * inv; }
.Lcm_nob_7:
	v_mfma_f32_16x16x32_bf16 v[18:21], v[170:173], v[82:85], v[18:21]
	s_nop 7
	v_swap_b32 v46, v50
	v_swap_b32 v50, v54
	v_swap_b32 v54, v58
	v_swap_b32 v47, v51
	v_swap_b32 v51, v55
	v_swap_b32 v55, v59
	v_swap_b32 v48, v52
	v_swap_b32 v52, v56
	v_swap_b32 v56, v60
	v_swap_b32 v49, v53
	v_swap_b32 v53, v57
	v_swap_b32 v57, v61
	v_swap_b32 v18, v22
	v_swap_b32 v22, v26
	v_swap_b32 v26, v104
	v_swap_b32 v19, v23
	v_swap_b32 v23, v27
	v_swap_b32 v27, v105
	v_swap_b32 v20, v24
	v_swap_b32 v24, v28
	v_swap_b32 v28, v106
	v_swap_b32 v21, v25
	v_swap_b32 v25, v29
	v_swap_b32 v29, v107
	v_add_u32_e32 v192, 0x4800, v192
	v_add_u32_e32 v193, 0x4800, v193
	s_add_i32 s4, s4, 1
	s_addk_i32 s5, 0x400
	s_cmp_lt_u32 s4, s26
	s_cbranch_scc1 .Lcm_top_3
.Lcm_rot_8:
	s_cmp_gt_u32 s4, 3
	s_cbranch_scc1 .Lcm_rotd_9
	v_swap_b32 v46, v50
	v_swap_b32 v50, v54
	v_swap_b32 v54, v58
	v_swap_b32 v47, v51
	v_swap_b32 v51, v55
	v_swap_b32 v55, v59
	v_swap_b32 v48, v52
	v_swap_b32 v52, v56
	v_swap_b32 v56, v60
	v_swap_b32 v49, v53
	v_swap_b32 v53, v57
	v_swap_b32 v57, v61
	v_swap_b32 v18, v22
	v_swap_b32 v22, v26
	v_swap_b32 v26, v104
	v_swap_b32 v19, v23
	v_swap_b32 v23, v27
	v_swap_b32 v27, v105
	v_swap_b32 v20, v24
	v_swap_b32 v24, v28
	v_swap_b32 v28, v106
	v_swap_b32 v21, v25
	v_swap_b32 v25, v29
	v_swap_b32 v29, v107
	s_add_i32 s4, s4, 1
	s_branch .Lcm_rot_8
.Lcm_rotd_9:
	s_waitcnt lgkmcnt(0)
	s_barrier
	v_max_f32_e32 v86, v138, v138
	v_max_f32_e32 v86, 0xda24260, v86
	v_div_scale_f32 v87, s[0:1], v86, v86, 1.0
	v_rcp_f32_e32 v88, v87
	s_nop 0
	v_fma_f32 v89, -v87, v88, 1.0
	v_fmac_f32_e32 v88, v89, v88
	v_div_scale_f32 v89, vcc, 1.0, v86, 1.0
	v_mul_f32_e32 v91, v89, v88
	v_fma_f32 v92, -v87, v91, v89
	v_fmac_f32_e32 v91, v92, v88
	v_fma_f32 v87, -v87, v91, v89
	v_div_fmas_f32 v87, v87, v88, v91
	v_div_fixup_f32 v68, v87, v86, 1.0
	v_lshlrev_b32_e32 v64, 16, v108
	v_add_f32_e32 v64, v110, v64
	v_mul_f32_e32 v64, 0xbfb8aa3b, v64
	v_exp_f32_e32 v64, v64
	s_nop 0
	v_add_f32_e32 v64, 1.0, v64
	v_rcp_f32_e32 v64, v64
	s_nop 0
	v_mul_f32_e32 v70, v68, v64
	v_pk_mul_f32 v[30:31], v[30:31], v[70:71] op_sel_hi:[1,0]
	v_pk_mul_f32 v[32:33], v[32:33], v[70:71] op_sel_hi:[1,0]
	global_store_dwordx4 v[124:125], v[30:33], off
	v_pk_mul_f32 v[34:35], v[34:35], v[70:71] op_sel_hi:[1,0]
	v_pk_mul_f32 v[36:37], v[36:37], v[70:71] op_sel_hi:[1,0]
	global_store_dwordx4 v[124:125], v[34:37], off offset:1024
	v_pk_mul_f32 v[38:39], v[38:39], v[70:71] op_sel_hi:[1,0]
	v_pk_mul_f32 v[40:41], v[40:41], v[70:71] op_sel_hi:[1,0]
	global_store_dwordx4 v[124:125], v[38:41], off offset:2048
	v_pk_mul_f32 v[42:43], v[42:43], v[70:71] op_sel_hi:[1,0]
	v_pk_mul_f32 v[44:45], v[44:45], v[70:71] op_sel_hi:[1,0]
	global_store_dwordx4 v[124:125], v[42:45], off offset:3072
	v_mov_b32_e32 v74, v156
	v_lshl_add_u32 v74, v74, 8, v150
	v_pk_mul_f32 v[46:47], v[46:47], v[68:69] op_sel_hi:[1,0]
	v_pk_mul_f32 v[48:49], v[48:49], v[68:69] op_sel_hi:[1,0]
	ds_write_b128 v74, v[46:49] offset:53248
	v_pk_mul_f32 v[50:51], v[50:51], v[68:69] op_sel_hi:[1,0]
	v_pk_mul_f32 v[52:53], v[52:53], v[68:69] op_sel_hi:[1,0]
	ds_write_b128 v74, v[50:53] offset:53312
	v_pk_mul_f32 v[54:55], v[54:55], v[68:69] op_sel_hi:[1,0]
	v_pk_mul_f32 v[56:57], v[56:57], v[68:69] op_sel_hi:[1,0]
	ds_write_b128 v74, v[54:57] offset:53376
	v_pk_mul_f32 v[58:59], v[58:59], v[68:69] op_sel_hi:[1,0]
	v_pk_mul_f32 v[60:61], v[60:61], v[68:69] op_sel_hi:[1,0]
	ds_write_b128 v74, v[58:61] offset:53440
	v_max_f32_e32 v86, v196, v196
	v_max_f32_e32 v86, 0xda24260, v86
	v_div_scale_f32 v87, s[0:1], v86, v86, 1.0
	v_rcp_f32_e32 v88, v87
	s_nop 0
	v_fma_f32 v89, -v87, v88, 1.0
	v_fmac_f32_e32 v88, v89, v88
	v_div_scale_f32 v89, vcc, 1.0, v86, 1.0
	v_mul_f32_e32 v91, v89, v88
	v_fma_f32 v92, -v87, v91, v89
	v_fmac_f32_e32 v91, v92, v88
	v_fma_f32 v87, -v87, v91, v89
	v_div_fmas_f32 v87, v87, v88, v91
	v_div_fixup_f32 v68, v87, v86, 1.0
	v_lshlrev_b32_e32 v64, 16, v109
	v_add_f32_e32 v64, v110, v64
	v_mul_f32_e32 v64, 0xbfb8aa3b, v64
	v_exp_f32_e32 v64, v64
	s_nop 0
	v_add_f32_e32 v64, 1.0, v64
	v_rcp_f32_e32 v64, v64
	s_nop 0
	v_mul_f32_e32 v70, v68, v64
	v_add_co_u32_e32 v72, vcc, 0x1000, v124
	s_nop 1
	v_addc_co_u32_e32 v73, vcc, 0, v125, vcc
	v_pk_mul_f32 v[174:175], v[174:175], v[70:71] op_sel_hi:[1,0]
	v_pk_mul_f32 v[176:177], v[176:177], v[70:71] op_sel_hi:[1,0]
	global_store_dwordx4 v[72:73], v[174:177], off
	v_pk_mul_f32 v[178:179], v[178:179], v[70:71] op_sel_hi:[1,0]
	v_pk_mul_f32 v[180:181], v[180:181], v[70:71] op_sel_hi:[1,0]
	global_store_dwordx4 v[72:73], v[178:181], off offset:1024
	v_pk_mul_f32 v[182:183], v[182:183], v[70:71] op_sel_hi:[1,0]
	v_pk_mul_f32 v[184:185], v[184:185], v[70:71] op_sel_hi:[1,0]
	global_store_dwordx4 v[72:73], v[182:185], off offset:2048
	v_pk_mul_f32 v[186:187], v[186:187], v[70:71] op_sel_hi:[1,0]
	v_pk_mul_f32 v[188:189], v[188:189], v[70:71] op_sel_hi:[1,0]
	global_store_dwordx4 v[72:73], v[186:189], off offset:3072
	v_or_b32_e32 v74, 16, v156
	v_lshl_add_u32 v74, v74, 8, v150
	v_pk_mul_f32 v[18:19], v[18:19], v[68:69] op_sel_hi:[1,0]
	v_pk_mul_f32 v[20:21], v[20:21], v[68:69] op_sel_hi:[1,0]
	ds_write_b128 v74, v[18:21] offset:53248
	v_pk_mul_f32 v[22:23], v[22:23], v[68:69] op_sel_hi:[1,0]
	v_pk_mul_f32 v[24:25], v[24:25], v[68:69] op_sel_hi:[1,0]
	ds_write_b128 v74, v[22:25] offset:53312
	v_pk_mul_f32 v[26:27], v[26:27], v[68:69] op_sel_hi:[1,0]
	v_pk_mul_f32 v[28:29], v[28:29], v[68:69] op_sel_hi:[1,0]
	ds_write_b128 v74, v[26:29] offset:53376
	v_pk_mul_f32 v[104:105], v[104:105], v[68:69] op_sel_hi:[1,0]
	v_pk_mul_f32 v[106:107], v[106:107], v[68:69] op_sel_hi:[1,0]
	ds_write_b128 v74, v[104:107] offset:53440
	v_lshlrev_b32_e32 v0, 1, v102
	v_lshlrev_b32_e32 v132, 1, v96
	s_branch .LBB0_361
